# prologue x pass: all eight rows of a wave loaded up front (pipelined loop for other grids)
# baseline (speedup 1.0000x reference)
; __device__ __forceinline__ unsigned cvt_pk_bf16(float lo, float hi) { unsigned r; asm volatile("v_cvt_pk_bf16_f32 %0, %1, %2" : "=v"(r) : "v"(lo), "v"(hi)); return r; }
; template <class T> __device__ __forceinline__ T* as_global(T* p) { return (T*)(GAS T*)p; }
; __device__ __forceinline__ float wave_sum(float v) {
; #pragma unroll
;     for (int o = 1; o < 64; o <<= 1) v += __shfl_xor(v, o);
;     return v;
; }
; __device__ __forceinline__ void prologue(const Args& a, LAS unsigned char* lds, int gw, int NGW, int wave, int lane, int nlayers) {
;     ...
;     for (int m = gw; m < MTOK; m += NGW) {
;         const f32x4* xr = (const f32x4*)(as_global(a.in[0]) + (size_t)m * DM) + lane;
;         u32x2* xb = (u32x2*)((bf16_t*)(ws + WS_XB) + (size_t)m * DM) + lane;
;         float s = 0.f; f32x4 xin[4];
; #pragma unroll
;         for (int j = 0; j < 4; ++j) xin[j] = xr[64 * j];
; #pragma unroll
;         for (int j = 0; j < 4; ++j) { const f32x4 v = xin[j]; s += (v[0] * v[0] + v[1] * v[1]) + (v[2] * v[2] + v[3] * v[3]);
;             u32x2 w; w.x = cvt_pk_bf16(v[0], v[1]); w.y = cvt_pk_bf16(v[2], v[3]); xb[64 * j] = w; }
;         s = wave_sum(s);
;         if (lane == 0) stats[m] = (i64)(s * FX);
;     }
.LBB0_152:
	s_cmpk_gt_i32 s20, 0x3fff
	s_cbranch_scc1 .LBB0_157
	s_load_dwordx2 s[4:5], s[0:1], 0x0
	s_ashr_i32 s21, s20, 31
	s_ashr_i32 s23, s22, 31
	s_lshl_b64 s[6:7], s[20:21], 11
	s_lshl_b64 s[8:9], s[20:21], 3
	s_lshl_b64 s[10:11], s[22:23], 3
	v_lshl_or_b32 v2, v1, 3, s6
	v_mov_b32_e32 v3, s7
	s_lshl_b64 s[12:13], s[22:23], 11
	s_lshl_b64 s[6:7], s[20:21], 12
	s_waitcnt lgkmcnt(0)
	s_add_u32 s4, s4, s6
	v_lshlrev_b32_e32 v4, 4, v1
	v_mov_b32_e32 v5, 0
	s_addc_u32 s5, s5, s7
	v_lshl_add_u64 v[6:7], s[4:5], 0, v[4:5]
	v_mbcnt_lo_u32_b32 v4, -1, 0
	v_mbcnt_hi_u32_b32 v4, -1, v4
	s_mov_b64 s[4:5], 0xc00
	v_and_b32_e32 v8, 64, v4
	v_cmp_eq_u32_e32 vcc, 0, v1
	v_lshl_add_u64 v[6:7], v[6:7], 0, s[4:5]
	s_lshl_b64 s[14:15], s[22:23], 12
	s_mov_b32 s3, 0xa400000
	v_add_u32_e32 v8, 64, v8
	v_xor_b32_e32 v9, 1, v4
	v_xor_b32_e32 v10, 2, v4
	v_xor_b32_e32 v11, 4, v4
	v_xor_b32_e32 v12, 8, v4
	v_xor_b32_e32 v13, 16, v4
	v_xor_b32_e32 v14, 32, v4
	s_mov_b32 s6, 0x2f800000
	s_mov_b32 s7, 0xcf800000
	s_mov_b32 s18, s20
	v_lshlrev_b32_e32 v170, 2, v9
	v_lshlrev_b32_e32 v171, 2, v10
	v_lshlrev_b32_e32 v172, 2, v11
	v_lshlrev_b32_e32 v173, 2, v12
	v_lshlrev_b32_e32 v174, 2, v13
	v_lshlrev_b32_e32 v175, 2, v14
	v_lshl_add_u64 v[176:177], s[94:95], 0, v[2:3]
	v_add_co_u32_e64 v176, s[4:5], s3, v176
	s_nop 1
	v_addc_co_u32_e64 v177, s[4:5], 0, v177, s[4:5]
	s_waitcnt lgkmcnt(0)
	s_cmpk_lg_i32 s70, 0x100
	s_cbranch_scc1 .Lxp_generic
	v_mov_b64_e32 v[178:179], v[6:7]
	global_load_dwordx4 v[16:19], v[178:179], off offset:-3072
	global_load_dwordx4 v[20:23], v[178:179], off offset:-2048
	global_load_dwordx4 v[24:27], v[178:179], off offset:-1024
	global_load_dwordx4 v[28:31], v[178:179], off
	v_lshl_add_u64 v[178:179], v[178:179], 0, s[14:15]
	global_load_dwordx4 v[32:35], v[178:179], off offset:-3072
	global_load_dwordx4 v[36:39], v[178:179], off offset:-2048
	global_load_dwordx4 v[40:43], v[178:179], off offset:-1024
	global_load_dwordx4 v[44:47], v[178:179], off
	v_lshl_add_u64 v[178:179], v[178:179], 0, s[14:15]
	global_load_dwordx4 v[48:51], v[178:179], off offset:-3072
	global_load_dwordx4 v[52:55], v[178:179], off offset:-2048
	global_load_dwordx4 v[56:59], v[178:179], off offset:-1024
	global_load_dwordx4 v[60:63], v[178:179], off
	v_lshl_add_u64 v[178:179], v[178:179], 0, s[14:15]
	global_load_dwordx4 v[64:67], v[178:179], off offset:-3072
	global_load_dwordx4 v[68:71], v[178:179], off offset:-2048
	global_load_dwordx4 v[72:75], v[178:179], off offset:-1024
	global_load_dwordx4 v[76:79], v[178:179], off
	v_lshl_add_u64 v[178:179], v[178:179], 0, s[14:15]
	global_load_dwordx4 v[80:83], v[178:179], off offset:-3072
	global_load_dwordx4 v[84:87], v[178:179], off offset:-2048
	global_load_dwordx4 v[88:91], v[178:179], off offset:-1024
	global_load_dwordx4 v[92:95], v[178:179], off
	v_lshl_add_u64 v[178:179], v[178:179], 0, s[14:15]
	global_load_dwordx4 v[96:99], v[178:179], off offset:-3072
	global_load_dwordx4 v[100:103], v[178:179], off offset:-2048
	global_load_dwordx4 v[104:107], v[178:179], off offset:-1024
	global_load_dwordx4 v[108:111], v[178:179], off
	v_lshl_add_u64 v[178:179], v[178:179], 0, s[14:15]
	global_load_dwordx4 v[112:115], v[178:179], off offset:-3072
	global_load_dwordx4 v[116:119], v[178:179], off offset:-2048
	global_load_dwordx4 v[120:123], v[178:179], off offset:-1024
	global_load_dwordx4 v[124:127], v[178:179], off
	v_lshl_add_u64 v[178:179], v[178:179], 0, s[14:15]
	global_load_dwordx4 v[136:139], v[178:179], off offset:-3072
	global_load_dwordx4 v[140:143], v[178:179], off offset:-2048
	global_load_dwordx4 v[144:147], v[178:179], off offset:-1024
	global_load_dwordx4 v[148:151], v[178:179], off
	s_waitcnt vmcnt(28)
	v_mul_f32_e32 v153, v17, v17
	v_mul_f32_e32 v154, v19, v19
	v_mul_f32_e32 v155, v21, v21
	v_mul_f32_e32 v156, v23, v23
	v_mul_f32_e32 v157, v25, v25
	v_mul_f32_e32 v158, v27, v27
	v_fmac_f32_e32 v153, v16, v16
	v_fmac_f32_e32 v154, v18, v18
	v_fmac_f32_e32 v155, v20, v20
	v_fmac_f32_e32 v156, v22, v22
	v_mul_f32_e32 v159, v29, v29
	v_mul_f32_e32 v160, v31, v31
	v_fmac_f32_e32 v157, v24, v24
	v_fmac_f32_e32 v158, v26, v26
	v_add_f32_e32 v153, v153, v154
	v_add_f32_e32 v154, v155, v156
	v_fmac_f32_e32 v159, v28, v28
	v_fmac_f32_e32 v160, v30, v30
	v_add_f32_e32 v155, v157, v158
	v_add_f32_e32 v153, v153, v154
	v_add_f32_e32 v156, v159, v160
	v_add_f32_e32 v153, v153, v155
	v_add_f32_e32 v153, v153, v156
	ds_bpermute_b32 v152, v170, v153
	v_cvt_pk_bf16_f32 v162, v16, v17
	v_cvt_pk_bf16_f32 v163, v18, v19
	v_cvt_pk_bf16_f32 v164, v20, v21
	v_cvt_pk_bf16_f32 v165, v22, v23
	v_cvt_pk_bf16_f32 v166, v24, v25
	v_cvt_pk_bf16_f32 v167, v26, v27
	v_cvt_pk_bf16_f32 v168, v28, v29
	v_cvt_pk_bf16_f32 v169, v30, v31
	global_store_dwordx2 v[176:177], v[162:163], off
	global_store_dwordx2 v[176:177], v[164:165], off offset:512
	global_store_dwordx2 v[176:177], v[166:167], off offset:1024
	global_store_dwordx2 v[176:177], v[168:169], off offset:1536
	s_waitcnt lgkmcnt(0)
	v_add_f32_e32 v152, v153, v152
	ds_bpermute_b32 v161, v171, v152
	s_waitcnt lgkmcnt(0)
	v_add_f32_e32 v152, v152, v161
	ds_bpermute_b32 v161, v172, v152
	s_waitcnt lgkmcnt(0)
	v_add_f32_e32 v152, v152, v161
	ds_bpermute_b32 v161, v173, v152
	s_waitcnt lgkmcnt(0)
	v_add_f32_e32 v152, v152, v161
	ds_bpermute_b32 v161, v174, v152
	s_waitcnt lgkmcnt(0)
	v_add_f32_e32 v152, v152, v161
	ds_bpermute_b32 v161, v175, v152
	s_and_saveexec_b64 s[16:17], vcc
	s_cbranch_execz .Lxp_skip_u0
	s_waitcnt lgkmcnt(0)
	v_add_f32_e32 v152, v152, v161
	v_mul_f32_e32 v152, 0x4b800000, v152
	v_trunc_f32_e32 v152, v152
	v_mul_f32_e64 v153, |v152|, s6
	v_floor_f32_e32 v153, v153
	v_fma_f32 v154, v153, s7, |v152|
	v_cvt_u32_f32_e32 v153, v153
	v_cvt_u32_f32_e32 v154, v154
	v_ashrrev_i32_e32 v152, 31, v152
	v_xor_b32_e32 v155, v153, v152
	v_xor_b32_e32 v156, v154, v152
	v_sub_co_u32_e64 v156, s[4:5], v156, v152
	s_nop 1
	v_subb_co_u32_e64 v157, s[4:5], v155, v152, s[4:5]
	s_add_u32 s4, s94, s8
	s_addc_u32 s5, s95, s9
	s_nop 2
	global_store_dwordx2 v5, v[156:157], s[4:5]
; __device__ __forceinline__ unsigned cvt_pk_bf16(float lo, float hi) { unsigned r; asm volatile("v_cvt_pk_bf16_f32 %0, %1, %2" : "=v"(r) : "v"(lo), "v"(hi)); return r; }
; template <class T> __device__ __forceinline__ T* as_global(T* p) { return (T*)(GAS T*)p; }
; __device__ __forceinline__ float wave_sum(float v) {
; #pragma unroll
;     for (int o = 1; o < 64; o <<= 1) v += __shfl_xor(v, o);
;     return v;
; }
; __device__ __forceinline__ void prologue(const Args& a, LAS unsigned char* lds, int gw, int NGW, int wave, int lane, int nlayers) {
;     ...
;     for (int m = gw; m < MTOK; m += NGW) {
;         const f32x4* xr = (const f32x4*)(as_global(a.in[0]) + (size_t)m * DM) + lane;
;         u32x2* xb = (u32x2*)((bf16_t*)(ws + WS_XB) + (size_t)m * DM) + lane;
;         float s = 0.f; f32x4 xin[4];
; #pragma unroll
;         for (int j = 0; j < 4; ++j) xin[j] = xr[64 * j];
; #pragma unroll
;         for (int j = 0; j < 4; ++j) { const f32x4 v = xin[j]; s += (v[0] * v[0] + v[1] * v[1]) + (v[2] * v[2] + v[3] * v[3]);
;             u32x2 w; w.x = cvt_pk_bf16(v[0], v[1]); w.y = cvt_pk_bf16(v[2], v[3]); xb[64 * j] = w; }
;         s = wave_sum(s);
;         if (lane == 0) stats[m] = (i64)(s * FX);
;     }
.Lxp_skip_u0:
	s_or_b64 exec, exec, s[16:17]
	s_waitcnt lgkmcnt(0)
	s_add_i32 s18, s18, s22
	s_add_u32 s8, s8, s10
	s_addc_u32 s9, s9, s11
	v_lshl_add_u64 v[176:177], v[176:177], 0, s[12:13]
	s_waitcnt vmcnt(29)
	v_mul_f32_e32 v153, v33, v33
	v_mul_f32_e32 v154, v35, v35
	v_mul_f32_e32 v155, v37, v37
	v_mul_f32_e32 v156, v39, v39
	v_mul_f32_e32 v157, v41, v41
	v_mul_f32_e32 v158, v43, v43
	v_fmac_f32_e32 v153, v32, v32
	v_fmac_f32_e32 v154, v34, v34
	v_fmac_f32_e32 v155, v36, v36
	v_fmac_f32_e32 v156, v38, v38
	v_mul_f32_e32 v159, v45, v45
	v_mul_f32_e32 v160, v47, v47
	v_fmac_f32_e32 v157, v40, v40
	v_fmac_f32_e32 v158, v42, v42
	v_add_f32_e32 v153, v153, v154
	v_add_f32_e32 v154, v155, v156
	v_fmac_f32_e32 v159, v44, v44
	v_fmac_f32_e32 v160, v46, v46
	v_add_f32_e32 v155, v157, v158
	v_add_f32_e32 v153, v153, v154
	v_add_f32_e32 v156, v159, v160
	v_add_f32_e32 v153, v153, v155
	v_add_f32_e32 v153, v153, v156
	ds_bpermute_b32 v152, v170, v153
	v_cvt_pk_bf16_f32 v162, v32, v33
	v_cvt_pk_bf16_f32 v163, v34, v35
	v_cvt_pk_bf16_f32 v164, v36, v37
	v_cvt_pk_bf16_f32 v165, v38, v39
	v_cvt_pk_bf16_f32 v166, v40, v41
	v_cvt_pk_bf16_f32 v167, v42, v43
	v_cvt_pk_bf16_f32 v168, v44, v45
	v_cvt_pk_bf16_f32 v169, v46, v47
	global_store_dwordx2 v[176:177], v[162:163], off
	global_store_dwordx2 v[176:177], v[164:165], off offset:512
	global_store_dwordx2 v[176:177], v[166:167], off offset:1024
	global_store_dwordx2 v[176:177], v[168:169], off offset:1536
	s_waitcnt lgkmcnt(0)
	v_add_f32_e32 v152, v153, v152
	ds_bpermute_b32 v161, v171, v152
	s_waitcnt lgkmcnt(0)
	v_add_f32_e32 v152, v152, v161
	ds_bpermute_b32 v161, v172, v152
	s_waitcnt lgkmcnt(0)
	v_add_f32_e32 v152, v152, v161
	ds_bpermute_b32 v161, v173, v152
	s_waitcnt lgkmcnt(0)
	v_add_f32_e32 v152, v152, v161
	ds_bpermute_b32 v161, v174, v152
	s_waitcnt lgkmcnt(0)
	v_add_f32_e32 v152, v152, v161
	ds_bpermute_b32 v161, v175, v152
	s_and_saveexec_b64 s[16:17], vcc
	s_cbranch_execz .Lxp_skip_u1
	s_waitcnt lgkmcnt(0)
	v_add_f32_e32 v152, v152, v161
	v_mul_f32_e32 v152, 0x4b800000, v152
	v_trunc_f32_e32 v152, v152
	v_mul_f32_e64 v153, |v152|, s6
	v_floor_f32_e32 v153, v153
	v_fma_f32 v154, v153, s7, |v152|
	v_cvt_u32_f32_e32 v153, v153
	v_cvt_u32_f32_e32 v154, v154
	v_ashrrev_i32_e32 v152, 31, v152
	v_xor_b32_e32 v155, v153, v152
	v_xor_b32_e32 v156, v154, v152
	v_sub_co_u32_e64 v156, s[4:5], v156, v152
	s_nop 1
	v_subb_co_u32_e64 v157, s[4:5], v155, v152, s[4:5]
	s_add_u32 s4, s94, s8
	s_addc_u32 s5, s95, s9
	s_nop 2
	global_store_dwordx2 v5, v[156:157], s[4:5]
.Lxp_skip_u1:
	s_or_b64 exec, exec, s[16:17]
	s_waitcnt lgkmcnt(0)
	s_add_i32 s18, s18, s22
	s_add_u32 s8, s8, s10
	s_addc_u32 s9, s9, s11
	v_lshl_add_u64 v[176:177], v[176:177], 0, s[12:13]
	s_waitcnt vmcnt(30)
	v_mul_f32_e32 v153, v49, v49
	v_mul_f32_e32 v154, v51, v51
	v_mul_f32_e32 v155, v53, v53
	v_mul_f32_e32 v156, v55, v55
	v_mul_f32_e32 v157, v57, v57
	v_mul_f32_e32 v158, v59, v59
	v_fmac_f32_e32 v153, v48, v48
	v_fmac_f32_e32 v154, v50, v50
	v_fmac_f32_e32 v155, v52, v52
	v_fmac_f32_e32 v156, v54, v54
	v_mul_f32_e32 v159, v61, v61
	v_mul_f32_e32 v160, v63, v63
	v_fmac_f32_e32 v157, v56, v56
	v_fmac_f32_e32 v158, v58, v58
	v_add_f32_e32 v153, v153, v154
	v_add_f32_e32 v154, v155, v156
	v_fmac_f32_e32 v159, v60, v60
	v_fmac_f32_e32 v160, v62, v62
	v_add_f32_e32 v155, v157, v158
	v_add_f32_e32 v153, v153, v154
	v_add_f32_e32 v156, v159, v160
	v_add_f32_e32 v153, v153, v155
	v_add_f32_e32 v153, v153, v156
	ds_bpermute_b32 v152, v170, v153
	v_cvt_pk_bf16_f32 v162, v48, v49
	v_cvt_pk_bf16_f32 v163, v50, v51
	v_cvt_pk_bf16_f32 v164, v52, v53
	v_cvt_pk_bf16_f32 v165, v54, v55
	v_cvt_pk_bf16_f32 v166, v56, v57
	v_cvt_pk_bf16_f32 v167, v58, v59
	v_cvt_pk_bf16_f32 v168, v60, v61
	v_cvt_pk_bf16_f32 v169, v62, v63
	global_store_dwordx2 v[176:177], v[162:163], off
	global_store_dwordx2 v[176:177], v[164:165], off offset:512
	global_store_dwordx2 v[176:177], v[166:167], off offset:1024
	global_store_dwordx2 v[176:177], v[168:169], off offset:1536
	s_waitcnt lgkmcnt(0)
	v_add_f32_e32 v152, v153, v152
	ds_bpermute_b32 v161, v171, v152
	s_waitcnt lgkmcnt(0)
	v_add_f32_e32 v152, v152, v161
	ds_bpermute_b32 v161, v172, v152
	s_waitcnt lgkmcnt(0)
	v_add_f32_e32 v152, v152, v161
	ds_bpermute_b32 v161, v173, v152
	s_waitcnt lgkmcnt(0)
	v_add_f32_e32 v152, v152, v161
	ds_bpermute_b32 v161, v174, v152
	s_waitcnt lgkmcnt(0)
	v_add_f32_e32 v152, v152, v161
	ds_bpermute_b32 v161, v175, v152
	s_and_saveexec_b64 s[16:17], vcc
	s_cbranch_execz .Lxp_skip_u2
	s_waitcnt lgkmcnt(0)
	v_add_f32_e32 v152, v152, v161
	v_mul_f32_e32 v152, 0x4b800000, v152
	v_trunc_f32_e32 v152, v152
	v_mul_f32_e64 v153, |v152|, s6
	v_floor_f32_e32 v153, v153
	v_fma_f32 v154, v153, s7, |v152|
	v_cvt_u32_f32_e32 v153, v153
	v_cvt_u32_f32_e32 v154, v154
	v_ashrrev_i32_e32 v152, 31, v152
	v_xor_b32_e32 v155, v153, v152
	v_xor_b32_e32 v156, v154, v152
	v_sub_co_u32_e64 v156, s[4:5], v156, v152
	s_nop 1
	v_subb_co_u32_e64 v157, s[4:5], v155, v152, s[4:5]
	s_add_u32 s4, s94, s8
	s_addc_u32 s5, s95, s9
	s_nop 2
	global_store_dwordx2 v5, v[156:157], s[4:5]
; __device__ __forceinline__ unsigned cvt_pk_bf16(float lo, float hi) { unsigned r; asm volatile("v_cvt_pk_bf16_f32 %0, %1, %2" : "=v"(r) : "v"(lo), "v"(hi)); return r; }
; template <class T> __device__ __forceinline__ T* as_global(T* p) { return (T*)(GAS T*)p; }
; __device__ __forceinline__ float wave_sum(float v) {
; #pragma unroll
;     for (int o = 1; o < 64; o <<= 1) v += __shfl_xor(v, o);
;     return v;
; }
; __device__ __forceinline__ void prologue(const Args& a, LAS unsigned char* lds, int gw, int NGW, int wave, int lane, int nlayers) {
;     ...
;     for (int m = gw; m < MTOK; m += NGW) {
;         const f32x4* xr = (const f32x4*)(as_global(a.in[0]) + (size_t)m * DM) + lane;
;         u32x2* xb = (u32x2*)((bf16_t*)(ws + WS_XB) + (size_t)m * DM) + lane;
;         float s = 0.f; f32x4 xin[4];
; #pragma unroll
;         for (int j = 0; j < 4; ++j) xin[j] = xr[64 * j];
; #pragma unroll
;         for (int j = 0; j < 4; ++j) { const f32x4 v = xin[j]; s += (v[0] * v[0] + v[1] * v[1]) + (v[2] * v[2] + v[3] * v[3]);
;             u32x2 w; w.x = cvt_pk_bf16(v[0], v[1]); w.y = cvt_pk_bf16(v[2], v[3]); xb[64 * j] = w; }
;         s = wave_sum(s);
;         if (lane == 0) stats[m] = (i64)(s * FX);
;     }
.Lxp_skip_u2:
	s_or_b64 exec, exec, s[16:17]
	s_waitcnt lgkmcnt(0)
	s_add_i32 s18, s18, s22
	s_add_u32 s8, s8, s10
	s_addc_u32 s9, s9, s11
	v_lshl_add_u64 v[176:177], v[176:177], 0, s[12:13]
	s_waitcnt vmcnt(31)
	v_mul_f32_e32 v153, v65, v65
	v_mul_f32_e32 v154, v67, v67
	v_mul_f32_e32 v155, v69, v69
	v_mul_f32_e32 v156, v71, v71
	v_mul_f32_e32 v157, v73, v73
	v_mul_f32_e32 v158, v75, v75
	v_fmac_f32_e32 v153, v64, v64
	v_fmac_f32_e32 v154, v66, v66
	v_fmac_f32_e32 v155, v68, v68
	v_fmac_f32_e32 v156, v70, v70
	v_mul_f32_e32 v159, v77, v77
	v_mul_f32_e32 v160, v79, v79
	v_fmac_f32_e32 v157, v72, v72
	v_fmac_f32_e32 v158, v74, v74
	v_add_f32_e32 v153, v153, v154
	v_add_f32_e32 v154, v155, v156
	v_fmac_f32_e32 v159, v76, v76
	v_fmac_f32_e32 v160, v78, v78
	v_add_f32_e32 v155, v157, v158
	v_add_f32_e32 v153, v153, v154
	v_add_f32_e32 v156, v159, v160
	v_add_f32_e32 v153, v153, v155
	v_add_f32_e32 v153, v153, v156
	ds_bpermute_b32 v152, v170, v153
	v_cvt_pk_bf16_f32 v162, v64, v65
	v_cvt_pk_bf16_f32 v163, v66, v67
	v_cvt_pk_bf16_f32 v164, v68, v69
	v_cvt_pk_bf16_f32 v165, v70, v71
	v_cvt_pk_bf16_f32 v166, v72, v73
	v_cvt_pk_bf16_f32 v167, v74, v75
	v_cvt_pk_bf16_f32 v168, v76, v77
	v_cvt_pk_bf16_f32 v169, v78, v79
	global_store_dwordx2 v[176:177], v[162:163], off
	global_store_dwordx2 v[176:177], v[164:165], off offset:512
	global_store_dwordx2 v[176:177], v[166:167], off offset:1024
	global_store_dwordx2 v[176:177], v[168:169], off offset:1536
	s_waitcnt lgkmcnt(0)
	v_add_f32_e32 v152, v153, v152
	ds_bpermute_b32 v161, v171, v152
	s_waitcnt lgkmcnt(0)
	v_add_f32_e32 v152, v152, v161
	ds_bpermute_b32 v161, v172, v152
	s_waitcnt lgkmcnt(0)
	v_add_f32_e32 v152, v152, v161
	ds_bpermute_b32 v161, v173, v152
	s_waitcnt lgkmcnt(0)
	v_add_f32_e32 v152, v152, v161
	ds_bpermute_b32 v161, v174, v152
	s_waitcnt lgkmcnt(0)
	v_add_f32_e32 v152, v152, v161
	ds_bpermute_b32 v161, v175, v152
	s_and_saveexec_b64 s[16:17], vcc
	s_cbranch_execz .Lxp_skip_u3
	s_waitcnt lgkmcnt(0)
	v_add_f32_e32 v152, v152, v161
	v_mul_f32_e32 v152, 0x4b800000, v152
	v_trunc_f32_e32 v152, v152
	v_mul_f32_e64 v153, |v152|, s6
	v_floor_f32_e32 v153, v153
	v_fma_f32 v154, v153, s7, |v152|
	v_cvt_u32_f32_e32 v153, v153
	v_cvt_u32_f32_e32 v154, v154
	v_ashrrev_i32_e32 v152, 31, v152
	v_xor_b32_e32 v155, v153, v152
	v_xor_b32_e32 v156, v154, v152
	v_sub_co_u32_e64 v156, s[4:5], v156, v152
	s_nop 1
	v_subb_co_u32_e64 v157, s[4:5], v155, v152, s[4:5]
	s_add_u32 s4, s94, s8
	s_addc_u32 s5, s95, s9
	s_nop 2
	global_store_dwordx2 v5, v[156:157], s[4:5]
.Lxp_skip_u3:
	s_or_b64 exec, exec, s[16:17]
	s_waitcnt lgkmcnt(0)
	s_add_i32 s18, s18, s22
	s_add_u32 s8, s8, s10
	s_addc_u32 s9, s9, s11
	v_lshl_add_u64 v[176:177], v[176:177], 0, s[12:13]
	s_waitcnt vmcnt(32)
	v_mul_f32_e32 v153, v81, v81
	v_mul_f32_e32 v154, v83, v83
	v_mul_f32_e32 v155, v85, v85
	v_mul_f32_e32 v156, v87, v87
	v_mul_f32_e32 v157, v89, v89
	v_mul_f32_e32 v158, v91, v91
	v_fmac_f32_e32 v153, v80, v80
	v_fmac_f32_e32 v154, v82, v82
	v_fmac_f32_e32 v155, v84, v84
	v_fmac_f32_e32 v156, v86, v86
	v_mul_f32_e32 v159, v93, v93
	v_mul_f32_e32 v160, v95, v95
	v_fmac_f32_e32 v157, v88, v88
	v_fmac_f32_e32 v158, v90, v90
	v_add_f32_e32 v153, v153, v154
	v_add_f32_e32 v154, v155, v156
	v_fmac_f32_e32 v159, v92, v92
	v_fmac_f32_e32 v160, v94, v94
	v_add_f32_e32 v155, v157, v158
	v_add_f32_e32 v153, v153, v154
	v_add_f32_e32 v156, v159, v160
	v_add_f32_e32 v153, v153, v155
	v_add_f32_e32 v153, v153, v156
	ds_bpermute_b32 v152, v170, v153
	v_cvt_pk_bf16_f32 v162, v80, v81
	v_cvt_pk_bf16_f32 v163, v82, v83
	v_cvt_pk_bf16_f32 v164, v84, v85
	v_cvt_pk_bf16_f32 v165, v86, v87
	v_cvt_pk_bf16_f32 v166, v88, v89
	v_cvt_pk_bf16_f32 v167, v90, v91
	v_cvt_pk_bf16_f32 v168, v92, v93
	v_cvt_pk_bf16_f32 v169, v94, v95
	global_store_dwordx2 v[176:177], v[162:163], off
	global_store_dwordx2 v[176:177], v[164:165], off offset:512
	global_store_dwordx2 v[176:177], v[166:167], off offset:1024
	global_store_dwordx2 v[176:177], v[168:169], off offset:1536
	s_waitcnt lgkmcnt(0)
	v_add_f32_e32 v152, v153, v152
	ds_bpermute_b32 v161, v171, v152
	s_waitcnt lgkmcnt(0)
	v_add_f32_e32 v152, v152, v161
	ds_bpermute_b32 v161, v172, v152
	s_waitcnt lgkmcnt(0)
	v_add_f32_e32 v152, v152, v161
	ds_bpermute_b32 v161, v173, v152
	s_waitcnt lgkmcnt(0)
	v_add_f32_e32 v152, v152, v161
	ds_bpermute_b32 v161, v174, v152
	s_waitcnt lgkmcnt(0)
	v_add_f32_e32 v152, v152, v161
	ds_bpermute_b32 v161, v175, v152
	s_and_saveexec_b64 s[16:17], vcc
	s_cbranch_execz .Lxp_skip_u4
	s_waitcnt lgkmcnt(0)
	v_add_f32_e32 v152, v152, v161
	v_mul_f32_e32 v152, 0x4b800000, v152
	v_trunc_f32_e32 v152, v152
	v_mul_f32_e64 v153, |v152|, s6
	v_floor_f32_e32 v153, v153
	v_fma_f32 v154, v153, s7, |v152|
	v_cvt_u32_f32_e32 v153, v153
	v_cvt_u32_f32_e32 v154, v154
	v_ashrrev_i32_e32 v152, 31, v152
	v_xor_b32_e32 v155, v153, v152
	v_xor_b32_e32 v156, v154, v152
	v_sub_co_u32_e64 v156, s[4:5], v156, v152
	s_nop 1
	v_subb_co_u32_e64 v157, s[4:5], v155, v152, s[4:5]
	s_add_u32 s4, s94, s8
	s_addc_u32 s5, s95, s9
	s_nop 2
	global_store_dwordx2 v5, v[156:157], s[4:5]
; __device__ __forceinline__ unsigned cvt_pk_bf16(float lo, float hi) { unsigned r; asm volatile("v_cvt_pk_bf16_f32 %0, %1, %2" : "=v"(r) : "v"(lo), "v"(hi)); return r; }
; template <class T> __device__ __forceinline__ T* as_global(T* p) { return (T*)(GAS T*)p; }
; __device__ __forceinline__ float wave_sum(float v) {
; #pragma unroll
;     for (int o = 1; o < 64; o <<= 1) v += __shfl_xor(v, o);
;     return v;
; }
; __device__ __forceinline__ void prologue(const Args& a, LAS unsigned char* lds, int gw, int NGW, int wave, int lane, int nlayers) {
;     ...
;     for (int m = gw; m < MTOK; m += NGW) {
;         const f32x4* xr = (const f32x4*)(as_global(a.in[0]) + (size_t)m * DM) + lane;
;         u32x2* xb = (u32x2*)((bf16_t*)(ws + WS_XB) + (size_t)m * DM) + lane;
;         float s = 0.f; f32x4 xin[4];
; #pragma unroll
;         for (int j = 0; j < 4; ++j) xin[j] = xr[64 * j];
; #pragma unroll
;         for (int j = 0; j < 4; ++j) { const f32x4 v = xin[j]; s += (v[0] * v[0] + v[1] * v[1]) + (v[2] * v[2] + v[3] * v[3]);
;             u32x2 w; w.x = cvt_pk_bf16(v[0], v[1]); w.y = cvt_pk_bf16(v[2], v[3]); xb[64 * j] = w; }
;         s = wave_sum(s);
;         if (lane == 0) stats[m] = (i64)(s * FX);
;     }
.Lxp_skip_u4:
	s_or_b64 exec, exec, s[16:17]
	s_waitcnt lgkmcnt(0)
	s_add_i32 s18, s18, s22
	s_add_u32 s8, s8, s10
	s_addc_u32 s9, s9, s11
	v_lshl_add_u64 v[176:177], v[176:177], 0, s[12:13]
	s_waitcnt vmcnt(33)
	v_mul_f32_e32 v153, v97, v97
	v_mul_f32_e32 v154, v99, v99
	v_mul_f32_e32 v155, v101, v101
	v_mul_f32_e32 v156, v103, v103
	v_mul_f32_e32 v157, v105, v105
	v_mul_f32_e32 v158, v107, v107
	v_fmac_f32_e32 v153, v96, v96
	v_fmac_f32_e32 v154, v98, v98
	v_fmac_f32_e32 v155, v100, v100
	v_fmac_f32_e32 v156, v102, v102
	v_mul_f32_e32 v159, v109, v109
	v_mul_f32_e32 v160, v111, v111
	v_fmac_f32_e32 v157, v104, v104
	v_fmac_f32_e32 v158, v106, v106
	v_add_f32_e32 v153, v153, v154
	v_add_f32_e32 v154, v155, v156
	v_fmac_f32_e32 v159, v108, v108
	v_fmac_f32_e32 v160, v110, v110
	v_add_f32_e32 v155, v157, v158
	v_add_f32_e32 v153, v153, v154
	v_add_f32_e32 v156, v159, v160
	v_add_f32_e32 v153, v153, v155
	v_add_f32_e32 v153, v153, v156
	ds_bpermute_b32 v152, v170, v153
	v_cvt_pk_bf16_f32 v162, v96, v97
	v_cvt_pk_bf16_f32 v163, v98, v99
	v_cvt_pk_bf16_f32 v164, v100, v101
	v_cvt_pk_bf16_f32 v165, v102, v103
	v_cvt_pk_bf16_f32 v166, v104, v105
	v_cvt_pk_bf16_f32 v167, v106, v107
	v_cvt_pk_bf16_f32 v168, v108, v109
	v_cvt_pk_bf16_f32 v169, v110, v111
	global_store_dwordx2 v[176:177], v[162:163], off
	global_store_dwordx2 v[176:177], v[164:165], off offset:512
	global_store_dwordx2 v[176:177], v[166:167], off offset:1024
	global_store_dwordx2 v[176:177], v[168:169], off offset:1536
	s_waitcnt lgkmcnt(0)
	v_add_f32_e32 v152, v153, v152
	ds_bpermute_b32 v161, v171, v152
	s_waitcnt lgkmcnt(0)
	v_add_f32_e32 v152, v152, v161
	ds_bpermute_b32 v161, v172, v152
	s_waitcnt lgkmcnt(0)
	v_add_f32_e32 v152, v152, v161
	ds_bpermute_b32 v161, v173, v152
	s_waitcnt lgkmcnt(0)
	v_add_f32_e32 v152, v152, v161
	ds_bpermute_b32 v161, v174, v152
	s_waitcnt lgkmcnt(0)
	v_add_f32_e32 v152, v152, v161
	ds_bpermute_b32 v161, v175, v152
	s_and_saveexec_b64 s[16:17], vcc
	s_cbranch_execz .Lxp_skip_u5
	s_waitcnt lgkmcnt(0)
	v_add_f32_e32 v152, v152, v161
	v_mul_f32_e32 v152, 0x4b800000, v152
	v_trunc_f32_e32 v152, v152
	v_mul_f32_e64 v153, |v152|, s6
	v_floor_f32_e32 v153, v153
	v_fma_f32 v154, v153, s7, |v152|
	v_cvt_u32_f32_e32 v153, v153
	v_cvt_u32_f32_e32 v154, v154
	v_ashrrev_i32_e32 v152, 31, v152
	v_xor_b32_e32 v155, v153, v152
	v_xor_b32_e32 v156, v154, v152
	v_sub_co_u32_e64 v156, s[4:5], v156, v152
	s_nop 1
	v_subb_co_u32_e64 v157, s[4:5], v155, v152, s[4:5]
	s_add_u32 s4, s94, s8
	s_addc_u32 s5, s95, s9
	s_nop 2
	global_store_dwordx2 v5, v[156:157], s[4:5]
.Lxp_skip_u5:
	s_or_b64 exec, exec, s[16:17]
	s_waitcnt lgkmcnt(0)
	s_add_i32 s18, s18, s22
	s_add_u32 s8, s8, s10
	s_addc_u32 s9, s9, s11
	v_lshl_add_u64 v[176:177], v[176:177], 0, s[12:13]
	s_waitcnt vmcnt(34)
	v_mul_f32_e32 v153, v113, v113
	v_mul_f32_e32 v154, v115, v115
	v_mul_f32_e32 v155, v117, v117
	v_mul_f32_e32 v156, v119, v119
	v_mul_f32_e32 v157, v121, v121
	v_mul_f32_e32 v158, v123, v123
	v_fmac_f32_e32 v153, v112, v112
	v_fmac_f32_e32 v154, v114, v114
	v_fmac_f32_e32 v155, v116, v116
	v_fmac_f32_e32 v156, v118, v118
	v_mul_f32_e32 v159, v125, v125
	v_mul_f32_e32 v160, v127, v127
	v_fmac_f32_e32 v157, v120, v120
	v_fmac_f32_e32 v158, v122, v122
	v_add_f32_e32 v153, v153, v154
	v_add_f32_e32 v154, v155, v156
	v_fmac_f32_e32 v159, v124, v124
	v_fmac_f32_e32 v160, v126, v126
	v_add_f32_e32 v155, v157, v158
	v_add_f32_e32 v153, v153, v154
	v_add_f32_e32 v156, v159, v160
	v_add_f32_e32 v153, v153, v155
	v_add_f32_e32 v153, v153, v156
	ds_bpermute_b32 v152, v170, v153
	v_cvt_pk_bf16_f32 v162, v112, v113
	v_cvt_pk_bf16_f32 v163, v114, v115
	v_cvt_pk_bf16_f32 v164, v116, v117
	v_cvt_pk_bf16_f32 v165, v118, v119
	v_cvt_pk_bf16_f32 v166, v120, v121
	v_cvt_pk_bf16_f32 v167, v122, v123
	v_cvt_pk_bf16_f32 v168, v124, v125
	v_cvt_pk_bf16_f32 v169, v126, v127
	global_store_dwordx2 v[176:177], v[162:163], off
	global_store_dwordx2 v[176:177], v[164:165], off offset:512
	global_store_dwordx2 v[176:177], v[166:167], off offset:1024
	global_store_dwordx2 v[176:177], v[168:169], off offset:1536
	s_waitcnt lgkmcnt(0)
	v_add_f32_e32 v152, v153, v152
	ds_bpermute_b32 v161, v171, v152
	s_waitcnt lgkmcnt(0)
	v_add_f32_e32 v152, v152, v161
	ds_bpermute_b32 v161, v172, v152
	s_waitcnt lgkmcnt(0)
	v_add_f32_e32 v152, v152, v161
	ds_bpermute_b32 v161, v173, v152
	s_waitcnt lgkmcnt(0)
	v_add_f32_e32 v152, v152, v161
	ds_bpermute_b32 v161, v174, v152
	s_waitcnt lgkmcnt(0)
	v_add_f32_e32 v152, v152, v161
	ds_bpermute_b32 v161, v175, v152
	s_and_saveexec_b64 s[16:17], vcc
	s_cbranch_execz .Lxp_skip_u6
	s_waitcnt lgkmcnt(0)
	v_add_f32_e32 v152, v152, v161
	v_mul_f32_e32 v152, 0x4b800000, v152
	v_trunc_f32_e32 v152, v152
	v_mul_f32_e64 v153, |v152|, s6
	v_floor_f32_e32 v153, v153
	v_fma_f32 v154, v153, s7, |v152|
	v_cvt_u32_f32_e32 v153, v153
	v_cvt_u32_f32_e32 v154, v154
	v_ashrrev_i32_e32 v152, 31, v152
	v_xor_b32_e32 v155, v153, v152
	v_xor_b32_e32 v156, v154, v152
	v_sub_co_u32_e64 v156, s[4:5], v156, v152
	s_nop 1
	v_subb_co_u32_e64 v157, s[4:5], v155, v152, s[4:5]
	s_add_u32 s4, s94, s8
	s_addc_u32 s5, s95, s9
	s_nop 2
	global_store_dwordx2 v5, v[156:157], s[4:5]
; __device__ __forceinline__ unsigned cvt_pk_bf16(float lo, float hi) { unsigned r; asm volatile("v_cvt_pk_bf16_f32 %0, %1, %2" : "=v"(r) : "v"(lo), "v"(hi)); return r; }
; template <class T> __device__ __forceinline__ T* as_global(T* p) { return (T*)(GAS T*)p; }
; __device__ __forceinline__ void prologue(const Args& a, LAS unsigned char* lds, int gw, int NGW, int wave, int lane, int nlayers) {
;     ...
;     for (int m = gw; m < MTOK; m += NGW) {
;         const f32x4* xr = (const f32x4*)(as_global(a.in[0]) + (size_t)m * DM) + lane;
;         u32x2* xb = (u32x2*)((bf16_t*)(ws + WS_XB) + (size_t)m * DM) + lane;
;         float s = 0.f; f32x4 xin[4];
; #pragma unroll
;         for (int j = 0; j < 4; ++j) xin[j] = xr[64 * j];
; #pragma unroll
;         for (int j = 0; j < 4; ++j) { const f32x4 v = xin[j]; s += (v[0] * v[0] + v[1] * v[1]) + (v[2] * v[2] + v[3] * v[3]);
;             u32x2 w; w.x = cvt_pk_bf16(v[0], v[1]); w.y = cvt_pk_bf16(v[2], v[3]); xb[64 * j] = w; }
;         s = wave_sum(s);
;         if (lane == 0) stats[m] = (i64)(s * FX);
;     }
.Lxp_skip_u6:
	s_or_b64 exec, exec, s[16:17]
	s_waitcnt lgkmcnt(0)
	s_add_i32 s18, s18, s22
	s_add_u32 s8, s8, s10
	s_addc_u32 s9, s9, s11
	v_lshl_add_u64 v[176:177], v[176:177], 0, s[12:13]
	s_waitcnt vmcnt(35)
	v_mul_f32_e32 v153, v137, v137
	v_mul_f32_e32 v154, v139, v139
	v_mul_f32_e32 v155, v141, v141
	v_mul_f32_e32 v156, v143, v143
	v_mul_f32_e32 v157, v145, v145
	v_mul_f32_e32 v158, v147, v147
	v_fmac_f32_e32 v153, v136, v136
	v_fmac_f32_e32 v154, v138, v138
	v_fmac_f32_e32 v155, v140, v140
	v_fmac_f32_e32 v156, v142, v142
	v_mul_f32_e32 v159, v149, v149
	v_mul_f32_e32 v160, v151, v151
	v_fmac_f32_e32 v157, v144, v144
	v_fmac_f32_e32 v158, v146, v146
	v_add_f32_e32 v153, v153, v154
	v_add_f32_e32 v154, v155, v156
	v_fmac_f32_e32 v159, v148, v148
	v_fmac_f32_e32 v160, v150, v150
	v_add_f32_e32 v155, v157, v158
	v_add_f32_e32 v153, v153, v154
	v_add_f32_e32 v156, v159, v160
	v_add_f32_e32 v153, v153, v155
	v_add_f32_e32 v153, v153, v156
	ds_bpermute_b32 v152, v170, v153
	v_cvt_pk_bf16_f32 v162, v136, v137
	v_cvt_pk_bf16_f32 v163, v138, v139
	v_cvt_pk_bf16_f32 v164, v140, v141
	v_cvt_pk_bf16_f32 v165, v142, v143
	v_cvt_pk_bf16_f32 v166, v144, v145
	v_cvt_pk_bf16_f32 v167, v146, v147
	v_cvt_pk_bf16_f32 v168, v148, v149
	v_cvt_pk_bf16_f32 v169, v150, v151
	global_store_dwordx2 v[176:177], v[162:163], off
	global_store_dwordx2 v[176:177], v[164:165], off offset:512
	global_store_dwordx2 v[176:177], v[166:167], off offset:1024
	global_store_dwordx2 v[176:177], v[168:169], off offset:1536
	s_waitcnt lgkmcnt(0)
	v_add_f32_e32 v152, v153, v152
	ds_bpermute_b32 v161, v171, v152
	s_waitcnt lgkmcnt(0)
	v_add_f32_e32 v152, v152, v161
	ds_bpermute_b32 v161, v172, v152
	s_waitcnt lgkmcnt(0)
	v_add_f32_e32 v152, v152, v161
	ds_bpermute_b32 v161, v173, v152
	s_waitcnt lgkmcnt(0)
	v_add_f32_e32 v152, v152, v161
	ds_bpermute_b32 v161, v174, v152
	s_waitcnt lgkmcnt(0)
	v_add_f32_e32 v152, v152, v161
	ds_bpermute_b32 v161, v175, v152
	s_and_saveexec_b64 s[16:17], vcc
	s_cbranch_execz .Lxp_skip_u7
	s_waitcnt lgkmcnt(0)
	v_add_f32_e32 v152, v152, v161
	v_mul_f32_e32 v152, 0x4b800000, v152
	v_trunc_f32_e32 v152, v152
	v_mul_f32_e64 v153, |v152|, s6
	v_floor_f32_e32 v153, v153
	v_fma_f32 v154, v153, s7, |v152|
	v_cvt_u32_f32_e32 v153, v153
	v_cvt_u32_f32_e32 v154, v154
	v_ashrrev_i32_e32 v152, 31, v152
	v_xor_b32_e32 v155, v153, v152
	v_xor_b32_e32 v156, v154, v152
	v_sub_co_u32_e64 v156, s[4:5], v156, v152
	s_nop 1
	v_subb_co_u32_e64 v157, s[4:5], v155, v152, s[4:5]
	s_add_u32 s4, s94, s8
	s_addc_u32 s5, s95, s9
	s_nop 2
	global_store_dwordx2 v5, v[156:157], s[4:5]
.Lxp_skip_u7:
	s_or_b64 exec, exec, s[16:17]
	s_waitcnt lgkmcnt(0)
	s_add_i32 s18, s18, s22
	s_add_u32 s8, s8, s10
	s_addc_u32 s9, s9, s11
	v_lshl_add_u64 v[176:177], v[176:177], 0, s[12:13]
	s_branch .LBB0_157
.Lxp_generic:
	global_load_dwordx4 v[16:19], v[6:7], off offset:-3072
	global_load_dwordx4 v[20:23], v[6:7], off offset:-2048
	global_load_dwordx4 v[24:27], v[6:7], off offset:-1024
	global_load_dwordx4 v[28:31], v[6:7], off
.Lxp_loop:
	s_add_i32 s4, s18, s22
	s_cmpk_gt_i32 s4, 0x3fff
	s_cselect_b32 s4, 0, s14
	s_cselect_b32 s5, 0, s15
	v_lshl_add_u64 v[44:45], v[6:7], 0, s[4:5]
	s_cbranch_scc1 .Lxp_last_a
	global_load_dwordx4 v[48:51], v[44:45], off offset:-3072
	global_load_dwordx4 v[52:55], v[44:45], off offset:-2048
	global_load_dwordx4 v[56:59], v[44:45], off offset:-1024
	global_load_dwordx4 v[60:63], v[44:45], off
	s_waitcnt vmcnt(4)
	s_branch .Lxp_go_a

; __device__ __forceinline__ unsigned cvt_pk_bf16(float lo, float hi) { unsigned r; asm volatile("v_cvt_pk_bf16_f32 %0, %1, %2" : "=v"(r) : "v"(lo), "v"(hi)); return r; }
; template <class T> __device__ __forceinline__ T* as_global(T* p) { return (T*)(GAS T*)p; }
; __device__ __forceinline__ void prologue(const Args& a, LAS unsigned char* lds, int gw, int NGW, int wave, int lane, int nlayers) {
;     ...
;     for (int m = gw; m < MTOK; m += NGW) {
;         const f32x4* xr = (const f32x4*)(as_global(a.in[0]) + (size_t)m * DM) + lane;
;         u32x2* xb = (u32x2*)((bf16_t*)(ws + WS_XB) + (size_t)m * DM) + lane;
;         float s = 0.f; f32x4 xin[4];
; #pragma unroll
;         for (int j = 0; j < 4; ++j) xin[j] = xr[64 * j];
; #pragma unroll
;         for (int j = 0; j < 4; ++j) { const f32x4 v = xin[j]; s += (v[0] * v[0] + v[1] * v[1]) + (v[2] * v[2] + v[3] * v[3]);
;             u32x2 w; w.x = cvt_pk_bf16(v[0], v[1]); w.y = cvt_pk_bf16(v[2], v[3]); xb[64 * j] = w; }
;         s = wave_sum(s);
;         if (lane == 0) stats[m] = (i64)(s * FX);
;     }
.Lxp_go_a:
	v_mul_f32_e32 v153, v17, v17
	v_mul_f32_e32 v154, v19, v19
	v_mul_f32_e32 v155, v21, v21
	v_mul_f32_e32 v156, v23, v23
	v_mul_f32_e32 v157, v25, v25
	v_mul_f32_e32 v158, v27, v27
	v_fmac_f32_e32 v153, v16, v16
	v_fmac_f32_e32 v154, v18, v18
	v_fmac_f32_e32 v155, v20, v20
	v_fmac_f32_e32 v156, v22, v22
	v_mul_f32_e32 v159, v29, v29
	v_mul_f32_e32 v160, v31, v31
	v_fmac_f32_e32 v157, v24, v24
	v_fmac_f32_e32 v158, v26, v26
	v_add_f32_e32 v153, v153, v154
	v_add_f32_e32 v154, v155, v156
	v_fmac_f32_e32 v159, v28, v28
	v_fmac_f32_e32 v160, v30, v30
	v_add_f32_e32 v155, v157, v158
	v_add_f32_e32 v153, v153, v154
	v_add_f32_e32 v156, v159, v160
	v_add_f32_e32 v153, v153, v155
	v_add_f32_e32 v153, v153, v156
	ds_bpermute_b32 v152, v170, v153
	v_cvt_pk_bf16_f32 v162, v16, v17
	v_cvt_pk_bf16_f32 v163, v18, v19
	v_cvt_pk_bf16_f32 v164, v20, v21
	v_cvt_pk_bf16_f32 v165, v22, v23
	v_cvt_pk_bf16_f32 v166, v24, v25
	v_cvt_pk_bf16_f32 v167, v26, v27
	v_cvt_pk_bf16_f32 v168, v28, v29
	v_cvt_pk_bf16_f32 v169, v30, v31
	global_store_dwordx2 v[176:177], v[162:163], off
	global_store_dwordx2 v[176:177], v[164:165], off offset:512
	global_store_dwordx2 v[176:177], v[166:167], off offset:1024
	global_store_dwordx2 v[176:177], v[168:169], off offset:1536
	s_waitcnt lgkmcnt(0)
	v_add_f32_e32 v152, v153, v152
	ds_bpermute_b32 v161, v171, v152
	s_waitcnt lgkmcnt(0)
	v_add_f32_e32 v152, v152, v161
	ds_bpermute_b32 v161, v172, v152
	s_waitcnt lgkmcnt(0)
	v_add_f32_e32 v152, v152, v161
	ds_bpermute_b32 v161, v173, v152
	s_waitcnt lgkmcnt(0)
	v_add_f32_e32 v152, v152, v161
	ds_bpermute_b32 v161, v174, v152
	s_waitcnt lgkmcnt(0)
	v_add_f32_e32 v152, v152, v161
	ds_bpermute_b32 v161, v175, v152
	s_and_saveexec_b64 s[16:17], vcc
	s_cbranch_execz .Lxp_skip_a
	s_waitcnt lgkmcnt(0)
	v_add_f32_e32 v152, v152, v161
	v_mul_f32_e32 v152, 0x4b800000, v152
	v_trunc_f32_e32 v152, v152
	v_mul_f32_e64 v153, |v152|, s6
	v_floor_f32_e32 v153, v153
	v_fma_f32 v154, v153, s7, |v152|
	v_cvt_u32_f32_e32 v153, v153
	v_cvt_u32_f32_e32 v154, v154
	v_ashrrev_i32_e32 v152, 31, v152
	v_xor_b32_e32 v155, v153, v152
	v_xor_b32_e32 v156, v154, v152
	v_sub_co_u32_e64 v156, s[4:5], v156, v152
	s_nop 1
	v_subb_co_u32_e64 v157, s[4:5], v155, v152, s[4:5]
	s_add_u32 s4, s94, s8
	s_addc_u32 s5, s95, s9
	s_nop 2
	global_store_dwordx2 v5, v[156:157], s[4:5]
.Lxp_skip_a:
	s_or_b64 exec, exec, s[16:17]
	s_waitcnt lgkmcnt(0)
	s_add_i32 s18, s18, s22
	s_add_u32 s8, s8, s10
	s_addc_u32 s9, s9, s11
	v_lshl_add_u64 v[176:177], v[176:177], 0, s[12:13]
	v_mov_b64_e32 v[6:7], v[44:45]
	s_cmpk_gt_i32 s18, 0x3fff
	s_cbranch_scc1 .LBB0_157
	s_add_i32 s4, s18, s22
	s_cmpk_gt_i32 s4, 0x3fff
	s_cselect_b32 s4, 0, s14
	s_cselect_b32 s5, 0, s15
	v_lshl_add_u64 v[44:45], v[6:7], 0, s[4:5]
	s_cbranch_scc1 .Lxp_last_b
	global_load_dwordx4 v[16:19], v[44:45], off offset:-3072
	global_load_dwordx4 v[20:23], v[44:45], off offset:-2048
	global_load_dwordx4 v[24:27], v[44:45], off offset:-1024
	global_load_dwordx4 v[28:31], v[44:45], off
	s_waitcnt vmcnt(4)
	s_branch .Lxp_go_b

; __device__ __forceinline__ unsigned cvt_pk_bf16(float lo, float hi) { unsigned r; asm volatile("v_cvt_pk_bf16_f32 %0, %1, %2" : "=v"(r) : "v"(lo), "v"(hi)); return r; }
; template <class T> __device__ __forceinline__ T* as_global(T* p) { return (T*)(GAS T*)p; }
; __device__ __forceinline__ void prologue(const Args& a, LAS unsigned char* lds, int gw, int NGW, int wave, int lane, int nlayers) {
;     ...
;     for (int m = gw; m < MTOK; m += NGW) {
;         const f32x4* xr = (const f32x4*)(as_global(a.in[0]) + (size_t)m * DM) + lane;
;         u32x2* xb = (u32x2*)((bf16_t*)(ws + WS_XB) + (size_t)m * DM) + lane;
;         float s = 0.f; f32x4 xin[4];
; #pragma unroll
;         for (int j = 0; j < 4; ++j) xin[j] = xr[64 * j];
; #pragma unroll
;         for (int j = 0; j < 4; ++j) { const f32x4 v = xin[j]; s += (v[0] * v[0] + v[1] * v[1]) + (v[2] * v[2] + v[3] * v[3]);
;             u32x2 w; w.x = cvt_pk_bf16(v[0], v[1]); w.y = cvt_pk_bf16(v[2], v[3]); xb[64 * j] = w; }
;         s = wave_sum(s);
;         if (lane == 0) stats[m] = (i64)(s * FX);
;     }
.Lxp_go_b:
	v_mul_f32_e32 v153, v49, v49
	v_mul_f32_e32 v154, v51, v51
	v_mul_f32_e32 v155, v53, v53
	v_mul_f32_e32 v156, v55, v55
	v_mul_f32_e32 v157, v57, v57
	v_mul_f32_e32 v158, v59, v59
	v_fmac_f32_e32 v153, v48, v48
	v_fmac_f32_e32 v154, v50, v50
	v_fmac_f32_e32 v155, v52, v52
	v_fmac_f32_e32 v156, v54, v54
	v_mul_f32_e32 v159, v61, v61
	v_mul_f32_e32 v160, v63, v63
	v_fmac_f32_e32 v157, v56, v56
	v_fmac_f32_e32 v158, v58, v58
	v_add_f32_e32 v153, v153, v154
	v_add_f32_e32 v154, v155, v156
	v_fmac_f32_e32 v159, v60, v60
	v_fmac_f32_e32 v160, v62, v62
	v_add_f32_e32 v155, v157, v158
	v_add_f32_e32 v153, v153, v154
	v_add_f32_e32 v156, v159, v160
	v_add_f32_e32 v153, v153, v155
	v_add_f32_e32 v153, v153, v156
	ds_bpermute_b32 v152, v170, v153
	v_cvt_pk_bf16_f32 v162, v48, v49
	v_cvt_pk_bf16_f32 v163, v50, v51
	v_cvt_pk_bf16_f32 v164, v52, v53
	v_cvt_pk_bf16_f32 v165, v54, v55
	v_cvt_pk_bf16_f32 v166, v56, v57
	v_cvt_pk_bf16_f32 v167, v58, v59
	v_cvt_pk_bf16_f32 v168, v60, v61
	v_cvt_pk_bf16_f32 v169, v62, v63
	global_store_dwordx2 v[176:177], v[162:163], off
	global_store_dwordx2 v[176:177], v[164:165], off offset:512
	global_store_dwordx2 v[176:177], v[166:167], off offset:1024
	global_store_dwordx2 v[176:177], v[168:169], off offset:1536
	s_waitcnt lgkmcnt(0)
	v_add_f32_e32 v152, v153, v152
	ds_bpermute_b32 v161, v171, v152
	s_waitcnt lgkmcnt(0)
	v_add_f32_e32 v152, v152, v161
	ds_bpermute_b32 v161, v172, v152
	s_waitcnt lgkmcnt(0)
	v_add_f32_e32 v152, v152, v161
	ds_bpermute_b32 v161, v173, v152
	s_waitcnt lgkmcnt(0)
	v_add_f32_e32 v152, v152, v161
	ds_bpermute_b32 v161, v174, v152
	s_waitcnt lgkmcnt(0)
	v_add_f32_e32 v152, v152, v161
	ds_bpermute_b32 v161, v175, v152
	s_and_saveexec_b64 s[16:17], vcc
	s_cbranch_execz .Lxp_skip_b
	s_waitcnt lgkmcnt(0)
	v_add_f32_e32 v152, v152, v161
	v_mul_f32_e32 v152, 0x4b800000, v152
	v_trunc_f32_e32 v152, v152
	v_mul_f32_e64 v153, |v152|, s6
	v_floor_f32_e32 v153, v153
	v_fma_f32 v154, v153, s7, |v152|
	v_cvt_u32_f32_e32 v153, v153
	v_cvt_u32_f32_e32 v154, v154
	v_ashrrev_i32_e32 v152, 31, v152
	v_xor_b32_e32 v155, v153, v152
	v_xor_b32_e32 v156, v154, v152
	v_sub_co_u32_e64 v156, s[4:5], v156, v152
	s_nop 1
	v_subb_co_u32_e64 v157, s[4:5], v155, v152, s[4:5]
	s_add_u32 s4, s94, s8
	s_addc_u32 s5, s95, s9
	s_nop 2
	global_store_dwordx2 v5, v[156:157], s[4:5]
.Lxp_skip_b:
	s_or_b64 exec, exec, s[16:17]
	s_waitcnt lgkmcnt(0)
	s_add_i32 s18, s18, s22
	s_add_u32 s8, s8, s10
	s_addc_u32 s9, s9, s11
	v_lshl_add_u64 v[176:177], v[176:177], 0, s[12:13]
	v_mov_b64_e32 v[6:7], v[44:45]
	s_cmpk_gt_i32 s18, 0x3fff
	s_cbranch_scc1 .LBB0_157
	s_branch .Lxp_loop
